# P5 fused-norm epilogue part C: 8 ssq row loads issued together, no per-group vmcnt(0)
# baseline (speedup 1.0000x reference)
;     __device__ __forceinline__ void operator()(f32x4 (&acc)[2][2][4][2], const Unit& u, int wr, int wc, int fr, int fq) const {
;     ...
;         f32x4 gv[2][2];
; #pragma unroll
;         for (int bj = 0; bj < 2; ++bj)
; #pragma unroll
;             for (int n = 0; n < 2; ++n) gv[bj][n] = *(const f32x4*)(gw + col0 + bj * HALF + n * 16);
; #pragma unroll
;         for (int ai = 0; ai < 2; ++ai)
; #pragma unroll
;             for (int m = 0; m < 4; ++m) { const int row = row0 + ai * HALF + m * 16; const size_t off = (size_t)row * 1024 + col0;
;                 const float ss = __hip_atomic_load(ssq + row, __ATOMIC_RELAXED, __HIP_MEMORY_SCOPE_AGENT);
;                 const float rstd = 1.0f / sqrtf(ss * (1.0f / 1024.0f) + eps);
; #pragma unroll
;                 for (int bj = 0; bj < 2; ++bj)
; #pragma unroll
;                     for (int n = 0; n < 2; ++n) *(f32x4*)(out + off + bj * HALF + n * 16) = acc[ai][bj][m][n] * rstd * gv[bj][n]; }
.LBB0_588:
	v_lshlrev_b64 v[174:175], 2, v[174:175]
	s_waitcnt lgkmcnt(0)
	v_lshl_add_u64 v[0:1], s[24:25], 0, v[174:175]
	global_load_dwordx4 v[12:15], v[0:1], off
	global_load_dwordx4 v[8:11], v[0:1], off offset:64
	global_load_dwordx4 v[4:7], v[0:1], off offset:512
	s_nop 0
	global_load_dwordx4 v[0:3], v[0:1], off offset:576
	s_nop 0
	global_load_dword v176, v[112:113], off sc1
	global_load_dword v197, v[112:113], off offset:64 sc1
	global_load_dword v198, v[112:113], off offset:128 sc1
	global_load_dword v199, v[112:113], off offset:192 sc1
	global_load_dword v200, v[112:113], off offset:512 sc1
	global_load_dword v201, v[112:113], off offset:576 sc1
	global_load_dword v202, v[112:113], off offset:640 sc1
	global_load_dword v203, v[112:113], off offset:704 sc1
	v_lshl_add_u64 v[140:141], s[26:27], 0, v[140:141]
	v_lshl_add_u64 v[140:141], v[140:141], 0, v[174:175]
	v_lshl_add_u64 v[116:117], s[26:27], 0, v[116:117]
	v_lshl_add_u64 v[98:99], s[26:27], 0, v[98:99]
	v_lshl_add_u64 v[82:83], s[26:27], 0, v[82:83]
	v_lshl_add_u64 v[64:65], s[26:27], 0, v[64:65]
	v_lshl_add_u64 v[48:49], s[26:27], 0, v[48:49]
	v_lshl_add_u64 v[34:35], s[26:27], 0, v[34:35]
	v_lshl_add_u64 v[32:33], s[26:27], 0, v[32:33]
	v_lshl_add_u64 v[32:33], v[32:33], 0, v[174:175]
	s_waitcnt vmcnt(0)
	v_fmamk_f32 v176, v176, 0x3a800000, v185
	v_mul_f32_e32 v177, 0x4f800000, v176
	v_cmp_gt_f32_e32 vcc, s67, v176
	s_nop 1
	v_cndmask_b32_e32 v176, v176, v177, vcc
	v_sqrt_f32_e32 v177, v176
	s_nop 0
	v_add_u32_e32 v187, -1, v177
	v_add_u32_e32 v188, 1, v177
	v_fma_f32 v189, -v187, v177, v176
	v_fma_f32 v190, -v188, v177, v176
	v_cmp_ge_f32_e64 s[8:9], 0, v189
	s_nop 1
	v_cndmask_b32_e64 v177, v177, v187, s[8:9]
	v_cmp_lt_f32_e64 s[8:9], 0, v190
	s_nop 1
	v_cndmask_b32_e64 v177, v177, v188, s[8:9]
	v_mul_f32_e32 v187, 0x37800000, v177
	v_cndmask_b32_e32 v177, v177, v187, vcc
	v_cmp_class_f32_e32 vcc, v176, v186
	s_nop 1
	v_cndmask_b32_e32 v176, v177, v176, vcc
	v_div_scale_f32 v177, s[8:9], v176, v176, 1.0
	v_rcp_f32_e32 v187, v177
	v_div_scale_f32 v188, vcc, 1.0, v176, 1.0
	v_fma_f32 v189, -v177, v187, 1.0
	v_fmac_f32_e32 v187, v189, v187
	v_mul_f32_e32 v189, v188, v187
	v_fma_f32 v190, -v177, v189, v188
	v_fmac_f32_e32 v189, v190, v187
	v_fma_f32 v177, -v177, v189, v188
	v_div_fmas_f32 v177, v177, v187, v189
	v_div_fixup_f32 v176, v177, v176, 1.0
	v_pk_mul_f32 v[172:173], v[172:173], v[176:177] op_sel_hi:[1,0]
	v_pk_mul_f32 v[170:171], v[170:171], v[176:177] op_sel_hi:[1,0]
	v_pk_mul_f32 v[188:189], v[168:169], v[176:177] op_sel_hi:[1,0]
	v_pk_mul_f32 v[190:191], v[166:167], v[176:177] op_sel_hi:[1,0]
	v_pk_mul_f32 v[160:161], v[160:161], v[176:177] op_sel_hi:[1,0]
	v_pk_mul_f32 v[156:157], v[156:157], v[176:177] op_sel_hi:[1,0]
	v_pk_mul_f32 v[152:153], v[152:153], v[176:177] op_sel_hi:[1,0]
	v_pk_mul_f32 v[144:145], v[144:145], v[176:177] op_sel_hi:[1,0]
	v_pk_mul_f32 v[168:169], v[14:15], v[170:171]
	v_pk_mul_f32 v[166:167], v[12:13], v[172:173]
	v_pk_mul_f32 v[172:173], v[10:11], v[190:191]
	v_pk_mul_f32 v[170:171], v[8:9], v[188:189]
	v_pk_mul_f32 v[190:191], v[6:7], v[156:157]
	v_pk_mul_f32 v[188:189], v[4:5], v[160:161]
	v_pk_mul_f32 v[194:195], v[2:3], v[144:145]
	v_pk_mul_f32 v[192:193], v[0:1], v[152:153]
	global_store_dwordx4 v[140:141], v[166:169], off
	global_store_dwordx4 v[140:141], v[170:173], off offset:64
	global_store_dwordx4 v[140:141], v[188:191], off offset:512
	global_store_dwordx4 v[140:141], v[192:195], off offset:576
	v_mov_b32_e32 v140, v197
	v_fmamk_f32 v140, v140, 0x3a800000, v185
	v_mul_f32_e32 v141, 0x4f800000, v140
	v_cmp_gt_f32_e32 vcc, s67, v140
	s_nop 1
	v_cndmask_b32_e32 v140, v140, v141, vcc
	v_sqrt_f32_e32 v141, v140
	s_nop 0
	v_add_u32_e32 v144, -1, v141
	v_add_u32_e32 v145, 1, v141
	v_fma_f32 v152, -v144, v141, v140
	v_fma_f32 v153, -v145, v141, v140
	v_cmp_ge_f32_e64 s[8:9], 0, v152
	s_nop 1
	v_cndmask_b32_e64 v141, v141, v144, s[8:9]
	v_cmp_lt_f32_e64 s[8:9], 0, v153
	s_nop 1
	v_cndmask_b32_e64 v141, v141, v145, s[8:9]
	v_mul_f32_e32 v144, 0x37800000, v141
	v_cndmask_b32_e32 v141, v141, v144, vcc
	v_cmp_class_f32_e32 vcc, v140, v186
	s_nop 1
	v_cndmask_b32_e32 v144, v141, v140, vcc
	v_div_scale_f32 v145, s[8:9], v144, v144, 1.0
	v_rcp_f32_e32 v152, v145
	v_lshl_add_u64 v[140:141], v[116:117], 0, v[174:175]
	v_div_scale_f32 v116, vcc, 1.0, v144, 1.0
	v_fma_f32 v117, -v145, v152, 1.0
	v_fmac_f32_e32 v152, v117, v152
	v_mul_f32_e32 v117, v116, v152
	v_fma_f32 v153, -v145, v117, v116
	v_fmac_f32_e32 v117, v153, v152
	v_fma_f32 v116, -v145, v117, v116
	v_div_fmas_f32 v116, v116, v152, v117
	v_div_fixup_f32 v116, v116, v144, 1.0
	v_pk_mul_f32 v[144:145], v[164:165], v[116:117] op_sel_hi:[1,0]
	v_pk_mul_f32 v[152:153], v[162:163], v[116:117] op_sel_hi:[1,0]
	v_pk_mul_f32 v[156:157], v[158:159], v[116:117] op_sel_hi:[1,0]
	v_pk_mul_f32 v[154:155], v[154:155], v[116:117] op_sel_hi:[1,0]
	v_pk_mul_f32 v[158:159], v[146:147], v[116:117] op_sel_hi:[1,0]
	v_pk_mul_f32 v[146:147], v[126:127], v[116:117] op_sel_hi:[1,0]
	v_pk_mul_f32 v[160:161], v[124:125], v[116:117] op_sel_hi:[1,0]
	v_pk_mul_f32 v[162:163], v[118:119], v[116:117] op_sel_hi:[1,0]
	v_pk_mul_f32 v[118:119], v[14:15], v[152:153]
	v_pk_mul_f32 v[116:117], v[12:13], v[144:145]
	v_pk_mul_f32 v[126:127], v[10:11], v[154:155]
	v_pk_mul_f32 v[124:125], v[8:9], v[156:157]
	v_pk_mul_f32 v[146:147], v[6:7], v[146:147]
	v_pk_mul_f32 v[144:145], v[4:5], v[158:159]
	v_pk_mul_f32 v[154:155], v[2:3], v[162:163]
	v_pk_mul_f32 v[152:153], v[0:1], v[160:161]
	global_store_dwordx4 v[140:141], v[116:119], off
	global_store_dwordx4 v[140:141], v[124:127], off offset:64
;     __device__ __forceinline__ void operator()(f32x4 (&acc)[2][2][4][2], const Unit& u, int wr, int wc, int fr, int fq) const {
;     ...
;         f32x4 gv[2][2];
; #pragma unroll
;         for (int bj = 0; bj < 2; ++bj)
; #pragma unroll
;             for (int n = 0; n < 2; ++n) gv[bj][n] = *(const f32x4*)(gw + col0 + bj * HALF + n * 16);
; #pragma unroll
;         for (int ai = 0; ai < 2; ++ai)
; #pragma unroll
;             for (int m = 0; m < 4; ++m) { const int row = row0 + ai * HALF + m * 16; const size_t off = (size_t)row * 1024 + col0;
;                 const float ss = __hip_atomic_load(ssq + row, __ATOMIC_RELAXED, __HIP_MEMORY_SCOPE_AGENT);
;                 const float rstd = 1.0f / sqrtf(ss * (1.0f / 1024.0f) + eps);
; #pragma unroll
;                 for (int bj = 0; bj < 2; ++bj)
; #pragma unroll
;                     for (int n = 0; n < 2; ++n) *(f32x4*)(out + off + bj * HALF + n * 16) = acc[ai][bj][m][n] * rstd * gv[bj][n]; }
	global_store_dwordx4 v[140:141], v[144:147], off offset:512
	global_store_dwordx4 v[140:141], v[152:155], off offset:576
	v_lshl_add_u64 v[126:127], v[98:99], 0, v[174:175]
	v_mov_b32_e32 v116, v198
	v_fmamk_f32 v116, v116, 0x3a800000, v185
	v_mul_f32_e32 v117, 0x4f800000, v116
	v_cmp_gt_f32_e32 vcc, s67, v116
	s_nop 1
	v_cndmask_b32_e32 v116, v116, v117, vcc
	v_sqrt_f32_e32 v117, v116
	s_nop 0
	v_add_u32_e32 v118, -1, v117
	v_add_u32_e32 v119, 1, v117
	v_fma_f32 v124, -v118, v117, v116
	v_fma_f32 v125, -v119, v117, v116
	v_cmp_ge_f32_e64 s[8:9], 0, v124
	s_nop 1
	v_cndmask_b32_e64 v117, v117, v118, s[8:9]
	v_cmp_lt_f32_e64 s[8:9], 0, v125
	s_nop 1
	v_cndmask_b32_e64 v117, v117, v119, s[8:9]
	v_mul_f32_e32 v118, 0x37800000, v117
	v_cndmask_b32_e32 v117, v117, v118, vcc
	v_cmp_class_f32_e32 vcc, v116, v186
	s_nop 1
	v_cndmask_b32_e32 v116, v117, v116, vcc
	v_div_scale_f32 v117, s[8:9], v116, v116, 1.0
	v_rcp_f32_e32 v118, v117
	v_div_scale_f32 v98, vcc, 1.0, v116, 1.0
	v_fma_f32 v99, -v117, v118, 1.0
	v_fmac_f32_e32 v118, v99, v118
	v_mul_f32_e32 v99, v98, v118
	v_fma_f32 v119, -v117, v99, v98
	v_fmac_f32_e32 v99, v119, v118
	v_fma_f32 v98, -v117, v99, v98
	v_div_fmas_f32 v98, v98, v118, v99
	v_div_fixup_f32 v98, v98, v116, 1.0
	v_pk_mul_f32 v[116:117], v[150:151], v[98:99] op_sel_hi:[1,0]
	v_pk_mul_f32 v[118:119], v[148:149], v[98:99] op_sel_hi:[1,0]
	v_pk_mul_f32 v[124:125], v[142:143], v[98:99] op_sel_hi:[1,0]
	v_pk_mul_f32 v[122:123], v[122:123], v[98:99] op_sel_hi:[1,0]
	v_pk_mul_f32 v[110:111], v[110:111], v[98:99] op_sel_hi:[1,0]
	v_pk_mul_f32 v[140:141], v[106:107], v[98:99] op_sel_hi:[1,0]
	v_pk_mul_f32 v[142:143], v[104:105], v[98:99] op_sel_hi:[1,0]
	v_pk_mul_f32 v[144:145], v[100:101], v[98:99] op_sel_hi:[1,0]
	v_pk_mul_f32 v[100:101], v[14:15], v[118:119]
	v_pk_mul_f32 v[98:99], v[12:13], v[116:117]
	v_pk_mul_f32 v[106:107], v[10:11], v[122:123]
	v_pk_mul_f32 v[104:105], v[8:9], v[124:125]
	v_pk_mul_f32 v[118:119], v[6:7], v[140:141]
	v_pk_mul_f32 v[116:117], v[4:5], v[110:111]
	v_pk_mul_f32 v[124:125], v[2:3], v[144:145]
	v_pk_mul_f32 v[122:123], v[0:1], v[142:143]
	global_store_dwordx4 v[126:127], v[98:101], off
	global_store_dwordx4 v[126:127], v[104:107], off offset:64
	global_store_dwordx4 v[126:127], v[116:119], off offset:512
	global_store_dwordx4 v[126:127], v[122:125], off offset:576
	v_mov_b32_e32 v98, v199
	v_fmamk_f32 v98, v98, 0x3a800000, v185
	v_mul_f32_e32 v99, 0x4f800000, v98
	v_cmp_gt_f32_e32 vcc, s67, v98
	s_nop 1
	v_cndmask_b32_e32 v98, v98, v99, vcc
	v_sqrt_f32_e32 v99, v98
	s_nop 0
	v_add_u32_e32 v100, -1, v99
	v_add_u32_e32 v101, 1, v99
	v_fma_f32 v104, -v100, v99, v98
	v_fma_f32 v105, -v101, v99, v98
	v_cmp_ge_f32_e64 s[8:9], 0, v104
	s_nop 1
	v_cndmask_b32_e64 v99, v99, v100, s[8:9]
	v_cmp_lt_f32_e64 s[8:9], 0, v105
	v_lshl_add_u64 v[104:105], v[82:83], 0, v[174:175]
	s_nop 0
	v_cndmask_b32_e64 v99, v99, v101, s[8:9]
	v_mul_f32_e32 v100, 0x37800000, v99
	v_cndmask_b32_e32 v99, v99, v100, vcc
	v_cmp_class_f32_e32 vcc, v98, v186
	s_nop 1
	v_cndmask_b32_e32 v98, v99, v98, vcc
	v_div_scale_f32 v99, s[8:9], v98, v98, 1.0
	v_rcp_f32_e32 v100, v99
	v_div_scale_f32 v82, vcc, 1.0, v98, 1.0
	v_fma_f32 v83, -v99, v100, 1.0
	v_fmac_f32_e32 v100, v83, v100
	v_mul_f32_e32 v83, v82, v100
	v_fma_f32 v101, -v99, v83, v82
	v_fmac_f32_e32 v83, v101, v100
	v_fma_f32 v82, -v99, v83, v82
	v_div_fmas_f32 v82, v82, v100, v83
	v_div_fixup_f32 v82, v82, v98, 1.0
	v_pk_mul_f32 v[98:99], v[120:121], v[82:83] op_sel_hi:[1,0]
	v_pk_mul_f32 v[100:101], v[114:115], v[82:83] op_sel_hi:[1,0]
	v_pk_mul_f32 v[106:107], v[108:109], v[82:83] op_sel_hi:[1,0]
	v_pk_mul_f32 v[102:103], v[102:103], v[82:83] op_sel_hi:[1,0]
	v_pk_mul_f32 v[96:97], v[96:97], v[82:83] op_sel_hi:[1,0]
	v_pk_mul_f32 v[108:109], v[90:91], v[82:83] op_sel_hi:[1,0]
	v_pk_mul_f32 v[110:111], v[88:89], v[82:83] op_sel_hi:[1,0]
	v_pk_mul_f32 v[114:115], v[84:85], v[82:83] op_sel_hi:[1,0]
	v_pk_mul_f32 v[84:85], v[14:15], v[100:101]
	v_pk_mul_f32 v[82:83], v[12:13], v[98:99]
	v_pk_mul_f32 v[90:91], v[10:11], v[102:103]
	v_pk_mul_f32 v[88:89], v[8:9], v[106:107]
	v_pk_mul_f32 v[98:99], v[6:7], v[108:109]
	v_pk_mul_f32 v[96:97], v[4:5], v[96:97]
	v_pk_mul_f32 v[102:103], v[2:3], v[114:115]
	v_pk_mul_f32 v[100:101], v[0:1], v[110:111]
	global_store_dwordx4 v[104:105], v[82:85], off
	global_store_dwordx4 v[104:105], v[88:91], off offset:64
	global_store_dwordx4 v[104:105], v[96:99], off offset:512
	global_store_dwordx4 v[104:105], v[100:103], off offset:576
	v_mov_b32_e32 v82, v200
	v_fmamk_f32 v82, v82, 0x3a800000, v185
	v_mul_f32_e32 v83, 0x4f800000, v82
	v_cmp_gt_f32_e32 vcc, s67, v82
	s_nop 1
	v_cndmask_b32_e32 v82, v82, v83, vcc
	v_sqrt_f32_e32 v83, v82
	s_nop 0
	v_add_u32_e32 v84, -1, v83
	v_add_u32_e32 v85, 1, v83
	v_fma_f32 v88, -v84, v83, v82
	v_fma_f32 v89, -v85, v83, v82
	v_cmp_ge_f32_e64 s[8:9], 0, v88
	s_nop 1
	v_cndmask_b32_e64 v83, v83, v84, s[8:9]
	v_cmp_lt_f32_e64 s[8:9], 0, v89
	v_lshl_add_u64 v[88:89], v[64:65], 0, v[174:175]
	s_nop 0
	v_cndmask_b32_e64 v83, v83, v85, s[8:9]
	v_mul_f32_e32 v84, 0x37800000, v83
	v_cndmask_b32_e32 v83, v83, v84, vcc
	v_cmp_class_f32_e32 vcc, v82, v186
	s_nop 1
	v_cndmask_b32_e32 v82, v83, v82, vcc
	v_div_scale_f32 v83, s[8:9], v82, v82, 1.0
	v_rcp_f32_e32 v84, v83
	v_div_scale_f32 v64, vcc, 1.0, v82, 1.0
	v_fma_f32 v65, -v83, v84, 1.0
	v_fmac_f32_e32 v84, v65, v84
	v_mul_f32_e32 v65, v64, v84
	v_fma_f32 v85, -v83, v65, v64
	v_fmac_f32_e32 v65, v85, v84
	v_fma_f32 v64, -v83, v65, v64
	v_div_fmas_f32 v64, v64, v84, v65
	v_div_fixup_f32 v64, v64, v82, 1.0
	v_pk_mul_f32 v[82:83], v[94:95], v[64:65] op_sel_hi:[1,0]
;     __device__ __forceinline__ void operator()(f32x4 (&acc)[2][2][4][2], const Unit& u, int wr, int wc, int fr, int fq) const {
;     ...
;         f32x4 gv[2][2];
; #pragma unroll
;         for (int bj = 0; bj < 2; ++bj)
; #pragma unroll
;             for (int n = 0; n < 2; ++n) gv[bj][n] = *(const f32x4*)(gw + col0 + bj * HALF + n * 16);
; #pragma unroll
;         for (int ai = 0; ai < 2; ++ai)
; #pragma unroll
;             for (int m = 0; m < 4; ++m) { const int row = row0 + ai * HALF + m * 16; const size_t off = (size_t)row * 1024 + col0;
;                 const float ss = __hip_atomic_load(ssq + row, __ATOMIC_RELAXED, __HIP_MEMORY_SCOPE_AGENT);
;                 const float rstd = 1.0f / sqrtf(ss * (1.0f / 1024.0f) + eps);
; #pragma unroll
;                 for (int bj = 0; bj < 2; ++bj)
; #pragma unroll
;                     for (int n = 0; n < 2; ++n) *(f32x4*)(out + off + bj * HALF + n * 16) = acc[ai][bj][m][n] * rstd * gv[bj][n]; }
	v_pk_mul_f32 v[84:85], v[92:93], v[64:65] op_sel_hi:[1,0]
	v_pk_mul_f32 v[86:87], v[86:87], v[64:65] op_sel_hi:[1,0]
	v_pk_mul_f32 v[80:81], v[80:81], v[64:65] op_sel_hi:[1,0]
	v_pk_mul_f32 v[78:79], v[78:79], v[64:65] op_sel_hi:[1,0]
	v_pk_mul_f32 v[90:91], v[72:73], v[64:65] op_sel_hi:[1,0]
	v_pk_mul_f32 v[92:93], v[70:71], v[64:65] op_sel_hi:[1,0]
	v_pk_mul_f32 v[94:95], v[66:67], v[64:65] op_sel_hi:[1,0]
	v_pk_mul_f32 v[66:67], v[14:15], v[84:85]
	v_pk_mul_f32 v[64:65], v[12:13], v[82:83]
	v_pk_mul_f32 v[72:73], v[10:11], v[80:81]
	v_pk_mul_f32 v[70:71], v[8:9], v[86:87]
	v_pk_mul_f32 v[80:81], v[6:7], v[90:91]
	v_pk_mul_f32 v[78:79], v[4:5], v[78:79]
	v_pk_mul_f32 v[84:85], v[2:3], v[94:95]
	v_pk_mul_f32 v[82:83], v[0:1], v[92:93]
	global_store_dwordx4 v[88:89], v[64:67], off
	global_store_dwordx4 v[88:89], v[70:73], off offset:64
	global_store_dwordx4 v[88:89], v[78:81], off offset:512
	global_store_dwordx4 v[88:89], v[82:85], off offset:576
	v_mov_b32_e32 v64, v201
	v_fmamk_f32 v64, v64, 0x3a800000, v185
	v_mul_f32_e32 v65, 0x4f800000, v64
	v_cmp_gt_f32_e32 vcc, s67, v64
	s_nop 1
	v_cndmask_b32_e32 v64, v64, v65, vcc
	v_sqrt_f32_e32 v65, v64
	s_nop 0
	v_add_u32_e32 v66, -1, v65
	v_add_u32_e32 v67, 1, v65
	v_fma_f32 v70, -v66, v65, v64
	v_fma_f32 v71, -v67, v65, v64
	v_cmp_ge_f32_e64 s[8:9], 0, v70
	s_nop 1
	v_cndmask_b32_e64 v65, v65, v66, s[8:9]
	v_cmp_lt_f32_e64 s[8:9], 0, v71
	v_lshl_add_u64 v[70:71], v[48:49], 0, v[174:175]
	s_nop 0
	v_cndmask_b32_e64 v65, v65, v67, s[8:9]
	v_mul_f32_e32 v66, 0x37800000, v65
	v_cndmask_b32_e32 v65, v65, v66, vcc
	v_cmp_class_f32_e32 vcc, v64, v186
	s_nop 1
	v_cndmask_b32_e32 v64, v65, v64, vcc
	v_div_scale_f32 v65, s[8:9], v64, v64, 1.0
	v_rcp_f32_e32 v66, v65
	v_div_scale_f32 v48, vcc, 1.0, v64, 1.0
	v_fma_f32 v49, -v65, v66, 1.0
	v_fmac_f32_e32 v66, v49, v66
	v_mul_f32_e32 v49, v48, v66
	v_fma_f32 v67, -v65, v49, v48
	v_fmac_f32_e32 v49, v67, v66
	v_fma_f32 v48, -v65, v49, v48
	v_div_fmas_f32 v48, v48, v66, v49
	v_div_fixup_f32 v48, v48, v64, 1.0
	v_pk_mul_f32 v[64:65], v[76:77], v[48:49] op_sel_hi:[1,0]
	v_pk_mul_f32 v[66:67], v[74:75], v[48:49] op_sel_hi:[1,0]
	v_pk_mul_f32 v[68:69], v[68:69], v[48:49] op_sel_hi:[1,0]
	v_pk_mul_f32 v[62:63], v[62:63], v[48:49] op_sel_hi:[1,0]
	v_pk_mul_f32 v[60:61], v[60:61], v[48:49] op_sel_hi:[1,0]
	v_pk_mul_f32 v[72:73], v[54:55], v[48:49] op_sel_hi:[1,0]
	v_pk_mul_f32 v[74:75], v[52:53], v[48:49] op_sel_hi:[1,0]
	v_pk_mul_f32 v[76:77], v[46:47], v[48:49] op_sel_hi:[1,0]
	v_pk_mul_f32 v[48:49], v[14:15], v[66:67]
	v_pk_mul_f32 v[46:47], v[12:13], v[64:65]
	v_pk_mul_f32 v[54:55], v[10:11], v[62:63]
	v_pk_mul_f32 v[52:53], v[8:9], v[68:69]
	v_pk_mul_f32 v[62:63], v[6:7], v[72:73]
	v_pk_mul_f32 v[60:61], v[4:5], v[60:61]
	v_pk_mul_f32 v[66:67], v[2:3], v[76:77]
	v_pk_mul_f32 v[64:65], v[0:1], v[74:75]
	global_store_dwordx4 v[70:71], v[46:49], off
	global_store_dwordx4 v[70:71], v[52:55], off offset:64
	global_store_dwordx4 v[70:71], v[60:63], off offset:512
	global_store_dwordx4 v[70:71], v[64:67], off offset:576
	v_mov_b32_e32 v46, v202
	v_fmamk_f32 v46, v46, 0x3a800000, v185
	v_mul_f32_e32 v47, 0x4f800000, v46
	v_cmp_gt_f32_e32 vcc, s67, v46
	s_nop 1
	v_cndmask_b32_e32 v46, v46, v47, vcc
	v_sqrt_f32_e32 v47, v46
	s_nop 0
	v_add_u32_e32 v48, -1, v47
	v_add_u32_e32 v49, 1, v47
	v_fma_f32 v52, -v48, v47, v46
	v_fma_f32 v53, -v49, v47, v46
	v_cmp_ge_f32_e64 s[8:9], 0, v52
	s_nop 1
	v_cndmask_b32_e64 v47, v47, v48, s[8:9]
	v_cmp_lt_f32_e64 s[8:9], 0, v53
	v_lshl_add_u64 v[52:53], v[34:35], 0, v[174:175]
	s_nop 0
	v_cndmask_b32_e64 v47, v47, v49, s[8:9]
	v_mul_f32_e32 v48, 0x37800000, v47
	v_cndmask_b32_e32 v47, v47, v48, vcc
;     __device__ __forceinline__ void operator()(f32x4 (&acc)[2][2][4][2], const Unit& u, int wr, int wc, int fr, int fq) const {
;     ...
;         f32x4 gv[2][2];
; #pragma unroll
;         for (int bj = 0; bj < 2; ++bj)
; #pragma unroll
;             for (int n = 0; n < 2; ++n) gv[bj][n] = *(const f32x4*)(gw + col0 + bj * HALF + n * 16);
; #pragma unroll
;         for (int ai = 0; ai < 2; ++ai)
; #pragma unroll
;             for (int m = 0; m < 4; ++m) { const int row = row0 + ai * HALF + m * 16; const size_t off = (size_t)row * 1024 + col0;
;                 const float ss = __hip_atomic_load(ssq + row, __ATOMIC_RELAXED, __HIP_MEMORY_SCOPE_AGENT);
;                 const float rstd = 1.0f / sqrtf(ss * (1.0f / 1024.0f) + eps);
; #pragma unroll
;                 for (int bj = 0; bj < 2; ++bj)
; #pragma unroll
;                     for (int n = 0; n < 2; ++n) *(f32x4*)(out + off + bj * HALF + n * 16) = acc[ai][bj][m][n] * rstd * gv[bj][n]; }
	v_cmp_class_f32_e32 vcc, v46, v186
	s_nop 1
	v_cndmask_b32_e32 v46, v47, v46, vcc
	v_div_scale_f32 v47, s[8:9], v46, v46, 1.0
	v_rcp_f32_e32 v48, v47
	v_div_scale_f32 v34, vcc, 1.0, v46, 1.0
	v_fma_f32 v35, -v47, v48, 1.0
	v_fmac_f32_e32 v48, v35, v48
	v_mul_f32_e32 v35, v34, v48
	v_fma_f32 v49, -v47, v35, v34
	v_fmac_f32_e32 v35, v49, v48
	v_fma_f32 v34, -v47, v35, v34
	v_div_fmas_f32 v34, v34, v48, v35
	v_div_fixup_f32 v34, v34, v46, 1.0
	v_pk_mul_f32 v[46:47], v[58:59], v[34:35] op_sel_hi:[1,0]
	v_pk_mul_f32 v[48:49], v[56:57], v[34:35] op_sel_hi:[1,0]
	v_pk_mul_f32 v[50:51], v[50:51], v[34:35] op_sel_hi:[1,0]
	v_pk_mul_f32 v[44:45], v[44:45], v[34:35] op_sel_hi:[1,0]
	v_pk_mul_f32 v[42:43], v[42:43], v[34:35] op_sel_hi:[1,0]
	v_pk_mul_f32 v[54:55], v[40:41], v[34:35] op_sel_hi:[1,0]
	v_pk_mul_f32 v[56:57], v[38:39], v[34:35] op_sel_hi:[1,0]
	v_pk_mul_f32 v[58:59], v[36:37], v[34:35] op_sel_hi:[1,0]
	v_pk_mul_f32 v[36:37], v[14:15], v[48:49]
	v_pk_mul_f32 v[34:35], v[12:13], v[46:47]
	v_pk_mul_f32 v[40:41], v[10:11], v[44:45]
	v_pk_mul_f32 v[38:39], v[8:9], v[50:51]
	v_pk_mul_f32 v[44:45], v[6:7], v[54:55]
	v_pk_mul_f32 v[42:43], v[4:5], v[42:43]
	v_pk_mul_f32 v[48:49], v[2:3], v[58:59]
	v_pk_mul_f32 v[46:47], v[0:1], v[56:57]
	global_store_dwordx4 v[52:53], v[34:37], off
	global_store_dwordx4 v[52:53], v[38:41], off offset:64
	global_store_dwordx4 v[52:53], v[42:45], off offset:512
	global_store_dwordx4 v[52:53], v[46:49], off offset:576
	v_mov_b32_e32 v34, v203
	v_fmamk_f32 v34, v34, 0x3a800000, v185
	v_mul_f32_e32 v35, 0x4f800000, v34
	v_cmp_gt_f32_e32 vcc, s67, v34
	s_nop 1
	v_cndmask_b32_e32 v34, v34, v35, vcc
	v_sqrt_f32_e32 v35, v34
	s_nop 0
	v_add_u32_e32 v36, -1, v35
	v_add_u32_e32 v37, 1, v35
	v_fma_f32 v38, -v36, v35, v34
	v_fma_f32 v39, -v37, v35, v34
	v_cmp_ge_f32_e64 s[8:9], 0, v38
	s_nop 1
	v_cndmask_b32_e64 v35, v35, v36, s[8:9]
	v_cmp_lt_f32_e64 s[8:9], 0, v39
	s_nop 1
	v_cndmask_b32_e64 v35, v35, v37, s[8:9]
	v_mul_f32_e32 v36, 0x37800000, v35
	v_cndmask_b32_e32 v35, v35, v36, vcc
	v_cmp_class_f32_e32 vcc, v34, v186
	s_nop 1
	v_cndmask_b32_e32 v34, v35, v34, vcc
	v_div_scale_f32 v35, s[8:9], v34, v34, 1.0
	v_rcp_f32_e32 v36, v35
	v_div_scale_f32 v37, vcc, 1.0, v34, 1.0
	v_fma_f32 v38, -v35, v36, 1.0
	v_fmac_f32_e32 v36, v38, v36
	v_mul_f32_e32 v38, v37, v36
	v_fma_f32 v39, -v35, v38, v37
	v_fmac_f32_e32 v38, v39, v36
	v_fma_f32 v35, -v35, v38, v37
	v_div_fmas_f32 v35, v35, v36, v38
	v_div_fixup_f32 v34, v35, v34, 1.0
	v_pk_mul_f32 v[26:27], v[26:27], v[34:35] op_sel_hi:[1,0]
	v_pk_mul_f32 v[20:21], v[20:21], v[34:35] op_sel_hi:[1,0]
	s_andn2_b64 vcc, exec, s[4:5]
	v_pk_mul_f32 v[24:25], v[24:25], v[34:35] op_sel_hi:[1,0]
	v_pk_mul_f32 v[18:19], v[18:19], v[34:35] op_sel_hi:[1,0]
	v_pk_mul_f32 v[22:23], v[22:23], v[34:35] op_sel_hi:[1,0]
	v_pk_mul_f32 v[16:17], v[16:17], v[34:35] op_sel_hi:[1,0]
	v_pk_mul_f32 v[30:31], v[30:31], v[34:35] op_sel_hi:[1,0]
	v_pk_mul_f32 v[28:29], v[28:29], v[34:35] op_sel_hi:[1,0]
	v_pk_mul_f32 v[14:15], v[14:15], v[20:21]
	v_pk_mul_f32 v[12:13], v[12:13], v[26:27]
	s_mov_b64 s[4:5], -1
	v_pk_mul_f32 v[10:11], v[10:11], v[18:19]
	v_pk_mul_f32 v[8:9], v[8:9], v[24:25]
	v_pk_mul_f32 v[6:7], v[6:7], v[16:17]
	v_pk_mul_f32 v[4:5], v[4:5], v[22:23]
	v_pk_mul_f32 v[2:3], v[2:3], v[28:29]
	v_pk_mul_f32 v[0:1], v[0:1], v[30:31]
	global_store_dwordx4 v[32:33], v[12:15], off
	global_store_dwordx4 v[32:33], v[8:11], off offset:64
	global_store_dwordx4 v[32:33], v[4:7], off offset:512
	global_store_dwordx4 v[32:33], v[0:3], off offset:576
	s_cbranch_vccnz .LBB0_550
	s_andn2_b64 vcc, exec, s[10:11]
	s_cbranch_vccnz .LBB0_549
	s_barrier
	s_branch .LBB0_549
